# P2: SGU-first / attention-first halves chosen by bit 3 of the virtual workgroup index (the eight workgroups sharing one head's K/V now run attention together)
# speedup vs baseline: 1.0561x; 1.0062x over previous
; #define PH_IDS() int tid = threadIdx.x; asm volatile("" : "+v"(tid)); const int lane = tid & 63
; __global__ void __launch_bounds__(NWAVES * 64, 2) fwd_mega(Args args) {
;     ...
;     if (IN(2)) {
;         const bf16* WSM = (const bf16*)(ws + WS_WSM);
;         const fa::Tensors FT{AO, KB, VB, ZB, cc};
;         if (vcu & 1) { fa::fox_phase((char*)lds_raw, FT, vcu, G); __syncthreads(); { PH_IDS(); v4u vin[4];
.LBB0_216:
	s_cmp_lt_i32 s30, 3
	s_cselect_b64 s[6:7], -1, 0
	s_and_b64 s[8:9], s[6:7], s[4:5]
	s_andn2_b64 vcc, exec, s[8:9]
	s_cbranch_vccnz .LBB0_324
	s_add_u32 s10, s28, 0x300000
	s_addc_u32 s11, s29, 0
	s_bitcmp0_b32 s86, 3
	s_mov_b64 s[4:5], -1
	s_cbranch_scc1 .LBB0_271

; #define PH_IDS() int tid = threadIdx.x; asm volatile("" : "+v"(tid)); const int lane = tid & 63
; __global__ void __launch_bounds__(NWAVES * 64, 2) fwd_mega(Args args) {
;     ...
;         if (vcu & 1) { fa::fox_phase((char*)lds_raw, FT, vcu, G); __syncthreads(); { PH_IDS(); v4u vin[4];
;                 if (vcu < 2048) { const v4u* vp = (const v4u*)(VA + (size_t)((vcu >> 3) * 128 + (tid >> 2)) * 1024 + (vcu & 7) * 128 + (tid & 3) * 32);
; #pragma unroll
;                     for (int i = 0; i < 4; ++i) vin[i] = vp[i]; }
;                 for (int it = vcu; it < 2048; it += G) { const int itn = it + G; sgu_item(lds, VA, AO, ZA, WSM, args.in[3], args.in[4], args.in[6], it >> 3, it & 7, tid, lane, wave, vin, itn >> 3, itn & 7, itn < 2048); } } }
;         else { { PH_IDS(); v4u vin[4];
;                 if (vcu < 2048) { const v4u* vp = (const v4u*)(VA + (size_t)((vcu >> 3) * 128 + (tid >> 2)) * 1024 + (vcu & 7) * 128 + (tid & 3) * 32);
; #pragma unroll
;                     for (int i = 0; i < 4; ++i) vin[i] = vp[i]; }
;                 for (int it = vcu; it < 2048; it += G) { const int itn = it + G; sgu_item(lds, VA, AO, ZA, WSM, args.in[3], args.in[4], args.in[6], it >> 3, it & 7, tid, lane, wave, vin, itn >> 3, itn & 7, itn < 2048); } } __syncthreads(); fa::fox_phase((char*)lds_raw, FT, vcu, G); }
.LBB0_263:
	s_waitcnt vmcnt(0)
	s_barrier
	s_bitcmp1_b32 s86, 3
	s_cbranch_scc0 .LBB0_324

; #define PH_IDS() int tid = threadIdx.x; asm volatile("" : "+v"(tid)); const int lane = tid & 63
; __global__ void __launch_bounds__(NWAVES * 64, 2) fwd_mega(Args args) {
;     ...
;                 for (int it = vcu; it < 2048; it += G) { const int itn = it + G; sgu_item(lds, VA, AO, ZA, WSM, args.in[3], args.in[4], args.in[6], it >> 3, it & 7, tid, lane, wave, vin, itn >> 3, itn & 7, itn < 2048); } } }
;         else { { PH_IDS(); v4u vin[4];
;                 if (vcu < 2048) { const v4u* vp = (const v4u*)(VA + (size_t)((vcu >> 3) * 128 + (tid >> 2)) * 1024 + (vcu & 7) * 128 + (tid & 3) * 32);
; #pragma unroll
;                     for (int i = 0; i < 4; ++i) vin[i] = vp[i]; }
;                 for (int it = vcu; it < 2048; it += G) { const int itn = it + G; sgu_item(lds, VA, AO, ZA, WSM, args.in[3], args.in[4], args.in[6], it >> 3, it & 7, tid, lane, wave, vin, itn >> 3, itn & 7, itn < 2048); } } __syncthreads(); fa::fox_phase((char*)lds_raw, FT, vcu, G); }
.Lsgu_done:
	s_bitcmp1_b32 s86, 3
	s_cbranch_scc1 .LBB0_324
	s_waitcnt vmcnt(0)
	s_barrier
	s_branch .Lattn_entry
